# attention inner loop: K and V LDS fragment reads batched ahead of their MFMAs, row-max shuffles via v_permlane16/32_swap instead of ds_bpermute; 8192-point FFT radix-2 stages batched (8 butterflies pe
# speedup vs baseline: 1.0063x; 1.0063x over previous
; __device__ __forceinline__ float2 twid(float turns) { return make_float2(__builtin_amdgcn_cosf(turns), __builtin_amdgcn_sinf(turns)); }
; __device__ __forceinline__ float2 cmul(float2 a, float2 b) { return make_float2(a.x * b.x - a.y * b.y, a.x * b.y + a.y * b.x); }
; __device__ __forceinline__ float2 cadd(float2 a, float2 b) { return make_float2(a.x + b.x, a.y + b.y); }
; __device__ __forceinline__ float2 csub(float2 a, float2 b) { return make_float2(a.x - b.x, a.y - b.y); }
; __device__ __forceinline__ void fft_fwd(float2* z, int lg, int tid) {
;     ...
;     if (lg & 1) {
;         const int h = 1 << lh, oh = h + (h >> 4);
;         for (int j = tid; j < h; j += 512) {
;             const int pj = PD(j);
;             const float2 a = z[pj], b = z[pj + oh];
;             z[pj] = cadd(a, b); z[pj + oh] = cmul(csub(a, b), twid(-(float)j * (0.5f / (float)h)));
;         }
;         __syncthreads();
.LBB0_608:
	s_or_b64 exec, exec, s[0:1]
	s_mov_b32 s12, 13
	s_add_i32 s0, s12, -1
	s_and_b32 s1, s12, 1
	s_bitcmp1_b32 s12, 0
	s_cselect_b64 s[8:9], -1, 0
	s_lshl_b32 s19, 1, s0
	s_cmp_eq_u32 s1, 0
	s_mov_b64 s[0:1], -1
	s_waitcnt lgkmcnt(0)
	s_barrier
	s_cbranch_scc1 .LBB0_613
	v_cmp_gt_i32_e32 vcc, s19, v103
	s_and_saveexec_b64 s[0:1], vcc
	s_cbranch_execz .LBB0_612
	v_cvt_f32_u32_e32 v0, s19
	s_lshl_b32 s10, s19, 3
	s_add_i32 s13, s10, 0
	s_lshr_b32 s10, s19, 1
	s_and_b32 s10, s10, 0x7ffffff8
	s_add_i32 s13, s13, s10
	v_div_scale_f32 v2, s[10:11], v0, v0, 0.5
	v_rcp_f32_e32 v3, v2
	s_mov_b64 s[10:11], 0
	v_fma_f32 v4, -v2, v3, 1.0
	v_fmac_f32_e32 v3, v4, v3
	v_div_scale_f32 v4, vcc, 0.5, v0, 0.5
	v_mul_f32_e32 v5, v4, v3
	v_fma_f32 v6, -v2, v5, v4
	v_fmac_f32_e32 v5, v6, v3
	v_fma_f32 v2, -v2, v5, v4
	v_div_fmas_f32 v2, v2, v3, v5
	v_div_fixup_f32 v0, v2, v0, 0.5
	v_mov_b32_e32 v2, v103
	s_cmpk_lg_u32 s19, 0x1000
	s_cbranch_scc1 .LBB0_611
	v_ashrrev_i32_e32 v151, 4, v103
	v_add_lshl_u32 v151, v103, v151, 3
	ds_read_b64 v[152:153], v151 offset:0
	ds_read_b64 v[154:155], v151 offset:34816
	ds_read_b64 v[156:157], v151 offset:4352
	ds_read_b64 v[158:159], v151 offset:39168
	ds_read_b64 v[160:161], v151 offset:8704
	ds_read_b64 v[162:163], v151 offset:43520
	ds_read_b64 v[164:165], v151 offset:13056
	ds_read_b64 v[166:167], v151 offset:47872
	ds_read_b64 v[168:169], v151 offset:17408
	ds_read_b64 v[170:171], v151 offset:52224
	ds_read_b64 v[172:173], v151 offset:21760
	ds_read_b64 v[174:175], v151 offset:56576
	ds_read_b64 v[176:177], v151 offset:26112
	ds_read_b64 v[178:179], v151 offset:60928
	ds_read_b64 v[180:181], v151 offset:30464
	ds_read_b64 v[182:183], v151 offset:65280
	v_cvt_f32_i32_e32 v226, v103
	v_mul_f32_e64 v223, v0, -v226
	v_cos_f32_e32 v184, v223
	v_sin_f32_e32 v185, v223
	v_add_f32_e32 v222, 0x44000000, v226
	v_mul_f32_e64 v223, v0, -v222
	v_cos_f32_e32 v186, v223
	v_sin_f32_e32 v187, v223
	v_add_f32_e32 v222, 0x44800000, v226
	v_mul_f32_e64 v223, v0, -v222
	v_cos_f32_e32 v188, v223
	v_sin_f32_e32 v189, v223
	v_add_f32_e32 v222, 0x44c00000, v226
	v_mul_f32_e64 v223, v0, -v222
	v_cos_f32_e32 v190, v223
	v_sin_f32_e32 v191, v223
	v_add_f32_e32 v222, 0x45000000, v226
	v_mul_f32_e64 v223, v0, -v222
	v_cos_f32_e32 v192, v223
	v_sin_f32_e32 v193, v223
	v_add_f32_e32 v222, 0x45200000, v226
	v_mul_f32_e64 v223, v0, -v222
	v_cos_f32_e32 v194, v223
	v_sin_f32_e32 v195, v223
	v_add_f32_e32 v222, 0x45400000, v226
	v_mul_f32_e64 v223, v0, -v222
	v_cos_f32_e32 v196, v223
	v_sin_f32_e32 v197, v223
	v_add_f32_e32 v222, 0x45600000, v226
	v_mul_f32_e64 v223, v0, -v222
	v_cos_f32_e32 v198, v223
	v_sin_f32_e32 v199, v223
	s_waitcnt lgkmcnt(0)
	v_pk_add_f32 v[206:207], v[152:153], v[154:155]
	v_pk_add_f32 v[152:153], v[152:153], v[154:155] neg_lo:[0,1] neg_hi:[0,1]
	ds_write_b64 v151, v[206:207] offset:0
	v_mul_f32_e32 v224, v185, v153
	v_mul_f32_e32 v225, v185, v152
	v_fma_f32 v154, v184, v152, -v224
	v_fma_f32 v155, v184, v153, v225
	ds_write_b64 v151, v[154:155] offset:34816
	v_pk_add_f32 v[208:209], v[156:157], v[158:159]
	v_pk_add_f32 v[156:157], v[156:157], v[158:159] neg_lo:[0,1] neg_hi:[0,1]
	ds_write_b64 v151, v[208:209] offset:4352
	v_mul_f32_e32 v224, v187, v157
	v_mul_f32_e32 v225, v187, v156
	v_fma_f32 v158, v186, v156, -v224
	v_fma_f32 v159, v186, v157, v225
	ds_write_b64 v151, v[158:159] offset:39168
	v_pk_add_f32 v[210:211], v[160:161], v[162:163]
	v_pk_add_f32 v[160:161], v[160:161], v[162:163] neg_lo:[0,1] neg_hi:[0,1]
	ds_write_b64 v151, v[210:211] offset:8704
	v_mul_f32_e32 v224, v189, v161
	v_mul_f32_e32 v225, v189, v160
	v_fma_f32 v162, v188, v160, -v224
	v_fma_f32 v163, v188, v161, v225
	ds_write_b64 v151, v[162:163] offset:43520
	v_pk_add_f32 v[212:213], v[164:165], v[166:167]
	v_pk_add_f32 v[164:165], v[164:165], v[166:167] neg_lo:[0,1] neg_hi:[0,1]
	ds_write_b64 v151, v[212:213] offset:13056
	v_mul_f32_e32 v224, v191, v165
	v_mul_f32_e32 v225, v191, v164
	v_fma_f32 v166, v190, v164, -v224
	v_fma_f32 v167, v190, v165, v225
	ds_write_b64 v151, v[166:167] offset:47872
	v_pk_add_f32 v[214:215], v[168:169], v[170:171]
	v_pk_add_f32 v[168:169], v[168:169], v[170:171] neg_lo:[0,1] neg_hi:[0,1]
	ds_write_b64 v151, v[214:215] offset:17408
	v_mul_f32_e32 v224, v193, v169
	v_mul_f32_e32 v225, v193, v168
	v_fma_f32 v170, v192, v168, -v224
	v_fma_f32 v171, v192, v169, v225
	ds_write_b64 v151, v[170:171] offset:52224
	v_pk_add_f32 v[216:217], v[172:173], v[174:175]
	v_pk_add_f32 v[172:173], v[172:173], v[174:175] neg_lo:[0,1] neg_hi:[0,1]
	ds_write_b64 v151, v[216:217] offset:21760
	v_mul_f32_e32 v224, v195, v173
	v_mul_f32_e32 v225, v195, v172
	v_fma_f32 v174, v194, v172, -v224
	v_fma_f32 v175, v194, v173, v225
	ds_write_b64 v151, v[174:175] offset:56576
	v_pk_add_f32 v[218:219], v[176:177], v[178:179]
	v_pk_add_f32 v[176:177], v[176:177], v[178:179] neg_lo:[0,1] neg_hi:[0,1]
	ds_write_b64 v151, v[218:219] offset:26112
	v_mul_f32_e32 v224, v197, v177
	v_mul_f32_e32 v225, v197, v176
	v_fma_f32 v178, v196, v176, -v224
	v_fma_f32 v179, v196, v177, v225
	ds_write_b64 v151, v[178:179] offset:60928
	v_pk_add_f32 v[220:221], v[180:181], v[182:183]
	v_pk_add_f32 v[180:181], v[180:181], v[182:183] neg_lo:[0,1] neg_hi:[0,1]
	ds_write_b64 v151, v[220:221] offset:30464
	v_mul_f32_e32 v224, v199, v181
	v_mul_f32_e32 v225, v199, v180
	v_fma_f32 v182, v198, v180, -v224
	v_fma_f32 v183, v198, v181, v225
	ds_write_b64 v151, v[182:183] offset:65280
	s_branch .LBB0_612

; __device__ __forceinline__ float2 twid(float turns) { return make_float2(__builtin_amdgcn_cosf(turns), __builtin_amdgcn_sinf(turns)); }
; __device__ __forceinline__ float2 cmul(float2 a, float2 b) { return make_float2(a.x * b.x - a.y * b.y, a.x * b.y + a.y * b.x); }
; __device__ __forceinline__ float2 cadd(float2 a, float2 b) { return make_float2(a.x + b.x, a.y + b.y); }
; __device__ __forceinline__ float2 csub(float2 a, float2 b) { return make_float2(a.x - b.x, a.y - b.y); }
; __device__ __forceinline__ void fft_inv(float2* z, int lg, int tid) {
;     ...
;     if (lg & 1) {
;         const int h = 1 << lh, oh = h + (h >> 4);
;         for (int j = tid; j < h; j += 512) {
;             const int pj = PD(j);
;             const float2 a = z[pj], b = cmul(z[pj + oh], twid((float)j * (0.5f / (float)h)));
;             z[pj] = cadd(a, b); z[pj + oh] = csub(a, b);
;         }
;         __syncthreads();
.LBB0_682:
	s_or_b64 exec, exec, s[0:1]
	s_andn2_b64 vcc, exec, s[8:9]
	s_mov_b64 s[0:1], -1
	s_waitcnt lgkmcnt(0)
	s_barrier
	s_cbranch_vccnz .LBB0_687
	s_and_saveexec_b64 s[0:1], s[4:5]
	s_cbranch_execz .LBB0_686
	v_add_u32_e32 v0, 0, v54
	s_mov_b64 s[4:5], 0
	v_mov_b32_e32 v2, v103
	v_ashrrev_i32_e32 v151, 4, v103
	v_lshl_add_u32 v151, v151, 3, v54
	ds_read_b64 v[152:153], v151 offset:0
	ds_read_b64 v[154:155], v151 offset:34816
	ds_read_b64 v[156:157], v151 offset:4352
	ds_read_b64 v[158:159], v151 offset:39168
	ds_read_b64 v[160:161], v151 offset:8704
	ds_read_b64 v[162:163], v151 offset:43520
	ds_read_b64 v[164:165], v151 offset:13056
	ds_read_b64 v[166:167], v151 offset:47872
	ds_read_b64 v[168:169], v151 offset:17408
	ds_read_b64 v[170:171], v151 offset:52224
	ds_read_b64 v[172:173], v151 offset:21760
	ds_read_b64 v[174:175], v151 offset:56576
	ds_read_b64 v[176:177], v151 offset:26112
	ds_read_b64 v[178:179], v151 offset:60928
	ds_read_b64 v[180:181], v151 offset:30464
	ds_read_b64 v[182:183], v151 offset:65280
	v_cvt_f32_i32_e32 v226, v103
	v_mul_f32_e32 v223, 0x39000000, v226
	v_cos_f32_e32 v184, v223
	v_sin_f32_e32 v185, v223
	v_add_f32_e32 v222, 0x44000000, v226
	v_mul_f32_e32 v223, 0x39000000, v222
	v_cos_f32_e32 v186, v223
	v_sin_f32_e32 v187, v223
	v_add_f32_e32 v222, 0x44800000, v226
	v_mul_f32_e32 v223, 0x39000000, v222
	v_cos_f32_e32 v188, v223
	v_sin_f32_e32 v189, v223
	v_add_f32_e32 v222, 0x44c00000, v226
	v_mul_f32_e32 v223, 0x39000000, v222
	v_cos_f32_e32 v190, v223
	v_sin_f32_e32 v191, v223
	v_add_f32_e32 v222, 0x45000000, v226
	v_mul_f32_e32 v223, 0x39000000, v222
	v_cos_f32_e32 v192, v223
	v_sin_f32_e32 v193, v223
	v_add_f32_e32 v222, 0x45200000, v226
	v_mul_f32_e32 v223, 0x39000000, v222
	v_cos_f32_e32 v194, v223
	v_sin_f32_e32 v195, v223
	v_add_f32_e32 v222, 0x45400000, v226
	v_mul_f32_e32 v223, 0x39000000, v222
	v_cos_f32_e32 v196, v223
	v_sin_f32_e32 v197, v223
	v_add_f32_e32 v222, 0x45600000, v226
	v_mul_f32_e32 v223, 0x39000000, v222
	v_cos_f32_e32 v198, v223
	v_sin_f32_e32 v199, v223
	s_waitcnt lgkmcnt(0)
	v_mul_f32_e32 v224, v185, v155
	v_mul_f32_e32 v225, v185, v154
	v_fma_f32 v222, v184, v154, -v224
	v_fma_f32 v223, v184, v155, v225
	v_pk_add_f32 v[206:207], v[152:153], v[222:223]
	v_pk_add_f32 v[154:155], v[152:153], v[222:223] neg_lo:[0,1] neg_hi:[0,1]
	ds_write_b64 v151, v[206:207] offset:0
	ds_write_b64 v151, v[154:155] offset:34816
	v_mul_f32_e32 v224, v187, v159
	v_mul_f32_e32 v225, v187, v158
	v_fma_f32 v222, v186, v158, -v224
	v_fma_f32 v223, v186, v159, v225
	v_pk_add_f32 v[208:209], v[156:157], v[222:223]
	v_pk_add_f32 v[158:159], v[156:157], v[222:223] neg_lo:[0,1] neg_hi:[0,1]
	ds_write_b64 v151, v[208:209] offset:4352
	ds_write_b64 v151, v[158:159] offset:39168
	v_mul_f32_e32 v224, v189, v163
	v_mul_f32_e32 v225, v189, v162
	v_fma_f32 v222, v188, v162, -v224
	v_fma_f32 v223, v188, v163, v225
	v_pk_add_f32 v[210:211], v[160:161], v[222:223]
	v_pk_add_f32 v[162:163], v[160:161], v[222:223] neg_lo:[0,1] neg_hi:[0,1]
	ds_write_b64 v151, v[210:211] offset:8704
	ds_write_b64 v151, v[162:163] offset:43520
	v_mul_f32_e32 v224, v191, v167
	v_mul_f32_e32 v225, v191, v166
	v_fma_f32 v222, v190, v166, -v224
	v_fma_f32 v223, v190, v167, v225
	v_pk_add_f32 v[212:213], v[164:165], v[222:223]
	v_pk_add_f32 v[166:167], v[164:165], v[222:223] neg_lo:[0,1] neg_hi:[0,1]
	ds_write_b64 v151, v[212:213] offset:13056
	ds_write_b64 v151, v[166:167] offset:47872
	v_mul_f32_e32 v224, v193, v171
	v_mul_f32_e32 v225, v193, v170
	v_fma_f32 v222, v192, v170, -v224
	v_fma_f32 v223, v192, v171, v225
	v_pk_add_f32 v[214:215], v[168:169], v[222:223]
	v_pk_add_f32 v[170:171], v[168:169], v[222:223] neg_lo:[0,1] neg_hi:[0,1]
	ds_write_b64 v151, v[214:215] offset:17408
	ds_write_b64 v151, v[170:171] offset:52224
	v_mul_f32_e32 v224, v195, v175
	v_mul_f32_e32 v225, v195, v174
	v_fma_f32 v222, v194, v174, -v224
	v_fma_f32 v223, v194, v175, v225
	v_pk_add_f32 v[216:217], v[172:173], v[222:223]
	v_pk_add_f32 v[174:175], v[172:173], v[222:223] neg_lo:[0,1] neg_hi:[0,1]
	ds_write_b64 v151, v[216:217] offset:21760
	ds_write_b64 v151, v[174:175] offset:56576
	v_mul_f32_e32 v224, v197, v179
	v_mul_f32_e32 v225, v197, v178
	v_fma_f32 v222, v196, v178, -v224
	v_fma_f32 v223, v196, v179, v225
	v_pk_add_f32 v[218:219], v[176:177], v[222:223]
	v_pk_add_f32 v[178:179], v[176:177], v[222:223] neg_lo:[0,1] neg_hi:[0,1]
	ds_write_b64 v151, v[218:219] offset:26112
	ds_write_b64 v151, v[178:179] offset:60928
	v_mul_f32_e32 v224, v199, v183
	v_mul_f32_e32 v225, v199, v182
	v_fma_f32 v222, v198, v182, -v224
	v_fma_f32 v223, v198, v183, v225
	v_pk_add_f32 v[220:221], v[180:181], v[222:223]
	v_pk_add_f32 v[182:183], v[180:181], v[222:223] neg_lo:[0,1] neg_hi:[0,1]
	ds_write_b64 v151, v[220:221] offset:30464
	ds_write_b64 v151, v[182:183] offset:65280
	s_branch .LBB0_686

; __device__ __forceinline__ void ph_attn(KP p, int l, unsigned char* sm, int wv) {
;     ...
;                 const int kk0 = 16 * wid + 32 * s;
;                 f32x4 st[2];
; #pragma unroll
;                 for (int kt = 0; kt < 2; ++kt) {
;                     st[kt] = (f32x4){0.f, 0.f, 0.f, 0.f};
; #pragma unroll
;                     for (int ks = 0; ks < 2; ++ks) {
;                         const bf16x8 kf = *(const bf16x8*)(Ks + (kk0 + 16 * kt + fr) * 72 + 32 * ks + 8 * fq);
;                         st[kt] = __builtin_amdgcn_mfma_f32_16x16x32_bf16(kf, qf[ks], st[kt], 0, 0, 0);
;                     }
;                 }
;                 float sv[2][4]; float mx = -1e30f;
;                 if (interior && s >= 1 && s <= 7) {
; #pragma unroll
;                     for (int kt = 0; kt < 2; ++kt)
; #pragma unroll
;                         for (int r = 0; r < 4; ++r) { sv[kt][r] = st[kt][r]; mx = fmaxf(mx, sv[kt][r]); }
;                 } else {
; #pragma unroll
;                     for (int kt = 0; kt < 2; ++kt)
; #pragma unroll
;                         for (int r = 0; r < 4; ++r) {
;                             const int kk = kk0 + 16 * kt + 4 * fq + r, d = kk - 128 - qi, prel = Q0rel + kk - 128;
;                             const bool valid = d >= -128 && d <= 128 && prel >= 0 && prel < L && kk < 384;
;                             sv[kt][r] = valid ? st[kt][r] : -1e30f;
;                             mx = fmaxf(mx, sv[kt][r]);
;                         }
;                 }
.LBB0_847:
	v_add_u32_e32 v164, 0, v160
	ds_read_b128 v[58:61], v164
	ds_read_b128 v[62:65], v164 offset:64
	ds_read_b128 v[224:227], v164 offset:2304
	ds_read_b128 v[164:167], v164 offset:2368
	s_mov_b64 s[2:3], -1
	s_and_b64 vcc, exec, s[36:37]
	s_waitcnt lgkmcnt(3)
	v_mfma_f32_16x16x32_bf16 v[58:61], v[58:61], v[38:41], 0
	s_waitcnt lgkmcnt(2)
	v_mfma_f32_16x16x32_bf16 v[58:61], v[62:65], v[34:37], v[58:61]
	s_waitcnt lgkmcnt(1)
	v_mfma_f32_16x16x32_bf16 v[62:65], v[224:227], v[38:41], 0
	s_waitcnt lgkmcnt(0)
	v_mfma_f32_16x16x32_bf16 v[62:65], v[164:167], v[34:37], v[62:65]
	s_cbranch_vccz .LBB0_849
	v_add_u32_e32 v164, s42, v144
	v_add_u32_e32 v172, s42, v158
	v_add_u32_e32 v165, 32, v164
	v_add_u32_e32 v166, 32, v172
	v_cmp_gt_i32_e64 s[2:3], s41, v166
	v_cmp_gt_i32_e32 vcc, s21, v165
	v_cmp_lt_i32_e64 s[18:19], s33, v166
	s_and_b64 s[2:3], vcc, s[2:3]
	v_add_u32_e32 v166, 33, v164
	v_add_u32_e32 v167, 33, v172
	s_and_b64 vcc, s[18:19], s[2:3]
	v_cmp_gt_i32_e64 s[2:3], s41, v167
	v_cmp_gt_i32_e64 s[18:19], s21, v166
	v_cndmask_b32_e32 v171, v243, v58, vcc
	v_cmp_lt_i32_e32 vcc, s33, v167
	s_and_b64 s[2:3], s[18:19], s[2:3]
	v_add_u32_e32 v167, 34, v164
	v_add_u32_e32 v168, 34, v172
	s_and_b64 vcc, vcc, s[2:3]
	v_cmp_gt_i32_e64 s[2:3], s41, v168
	v_cmp_gt_i32_e64 s[18:19], s21, v167
	v_cndmask_b32_e32 v170, v243, v59, vcc
	v_cmp_lt_i32_e32 vcc, s33, v168
	s_and_b64 s[2:3], s[18:19], s[2:3]
	v_add_u32_e32 v164, 35, v164
	v_add_u32_e32 v167, 35, v172
	s_and_b64 vcc, vcc, s[2:3]
	v_cmp_gt_i32_e64 s[2:3], s41, v167
	v_cmp_gt_i32_e64 s[18:19], s21, v164
	v_cndmask_b32_e32 v169, v243, v60, vcc
	v_cmp_lt_i32_e32 vcc, s33, v167
	s_and_b64 s[2:3], s[18:19], s[2:3]
	s_and_b64 vcc, vcc, s[2:3]
	v_max3_f32 v166, v171, s35, v170
	v_cndmask_b32_e32 v168, v243, v61, vcc
	v_max3_f32 v164, v166, v169, v168
	v_add_u32_e32 v166, 48, v172
	v_cmp_gt_i32_e64 s[2:3], s41, v166
	v_cmp_gt_i32_e64 s[18:19], s46, v165
	v_cmp_lt_i32_e32 vcc, s33, v166
	s_and_b64 s[2:3], s[18:19], s[2:3]
	v_add_u32_e32 v167, 49, v172
	s_and_b64 vcc, vcc, s[2:3]
	v_cmp_gt_i32_e64 s[2:3], s41, v167
	v_cmp_gt_i32_e64 s[18:19], s47, v165
	v_cndmask_b32_e32 v166, v243, v62, vcc
	v_cmp_lt_i32_e32 vcc, s33, v167
	s_and_b64 s[2:3], s[18:19], s[2:3]
	s_and_b64 vcc, vcc, s[2:3]
	v_cndmask_b32_e32 v167, v243, v63, vcc
	v_max3_f32 v173, v164, v166, v167
	v_add_u32_e32 v164, 50, v172
	v_cmp_gt_i32_e64 s[2:3], s41, v164
	v_cmp_gt_i32_e64 s[18:19], s48, v165
	v_cmp_lt_i32_e32 vcc, s33, v164
	s_and_b64 s[2:3], s[18:19], s[2:3]
	v_add_u32_e32 v172, 51, v172
	s_and_b64 vcc, vcc, s[2:3]
	v_cmp_gt_i32_e64 s[2:3], s41, v172
	v_cmp_gt_i32_e64 s[18:19], s49, v165
	v_cndmask_b32_e32 v164, v243, v64, vcc
	v_cmp_lt_i32_e32 vcc, s33, v172
	s_and_b64 s[2:3], s[18:19], s[2:3]
	s_and_b64 vcc, vcc, s[2:3]
	v_cndmask_b32_e32 v165, v243, v65, vcc
	v_max3_f32 v172, v173, v164, v165
	s_mov_b64 s[2:3], 0

; __device__ __forceinline__ unsigned pk2(float lo, float hi) { unsigned r; asm volatile("v_cvt_pk_bf16_f32 %0, %1, %2" : "=v"(r) : "v"(lo), "v"(hi)); return r; }
; __device__ __forceinline__ float shx(float v, int mask, int lane) { return __int_as_float(__builtin_amdgcn_ds_bpermute((lane ^ mask) << 2, __float_as_int(v))); }
; __device__ __forceinline__ void ph_attn(KP p, int l, unsigned char* sm, int wv) {
;     ...
;                 mx = fmaxf(mx, shx(mx, 16, lane)); mx = fmaxf(mx, shx(mx, 32, lane));
;                 const float mn = fmaxf(mrun, mx), alpha = __builtin_amdgcn_exp2f(mrun - mn);
;                 mrun = mn;
;                 float pr[2][4], psum = 0.f;
; #pragma unroll
;                 for (int kt = 0; kt < 2; ++kt)
; #pragma unroll
;                     for (int r = 0; r < 4; ++r) { pr[kt][r] = __builtin_amdgcn_exp2f(sv[kt][r] - mn); psum += pr[kt][r]; }
;                 lsum = lsum * alpha + psum;
;                 const bool rescale = __builtin_amdgcn_ballot_w64(alpha != 1.0f) != 0ull;
;                 union { bf16x8 v; unsigned u[4]; } pf;
;                 pf.u[0] = pk2(pr[0][0], pr[0][1]); pf.u[1] = pk2(pr[0][2], pr[0][3]); pf.u[2] = pk2(pr[1][0], pr[1][1]); pf.u[3] = pk2(pr[1][2], pr[1][3]);
; #pragma unroll
;                 for (int dt = 0; dt < 4; ++dt) {
;                     if (rescale) o[dt] = o[dt] * alpha;
;                     union { bf16x8 v; u32x2 h[2]; } vf;
;                     vf.h[0] = *(const u32x2*)(Vt + (16 * dt + fr) * 404 + kk0 + 4 * fq);
;                     vf.h[1] = *(const u32x2*)(Vt + (16 * dt + fr) * 404 + kk0 + 16 + 4 * fq);
;                     o[dt] = __builtin_amdgcn_mfma_f32_16x16x32_bf16(vf.v, pf.v, o[dt], 0, 0, 0);
;                 }
.LBB0_851:
	v_max_f32_e32 v59, v172, v172
	v_mov_b32_e32 v58, v59
	v_add_u32_e32 v172, 0, v161
	v_add_u32_e32 v222, 0xe000, v172
	ds_read2_b64 v[206:209], v222 offset0:40 offset1:44
	ds_read_b64 v[210:211], v222 offset:13248
	ds_read_b64 v[212:213], v222 offset:13280
	ds_read_b64 v[214:215], v222 offset:26176
	ds_read_b64 v[216:217], v222 offset:26208
	ds_read_b64 v[218:219], v222 offset:39104
	ds_read_b64 v[220:221], v222 offset:39136
	v_permlane16_swap_b32_e32 v59, v58
	v_add_u32_e32 v161, 64, v161
	v_add_u32_e32 v160, 0x1200, v160
	v_max_f32_e32 v58, v59, v58
	v_mov_b32_e32 v59, v58
	s_nop 1
	v_permlane32_swap_b32_e32 v58, v59
	s_nop 0
	v_max3_f32 v63, v163, v58, v59
	v_sub_f32_e32 v59, v171, v63
	v_exp_f32_e32 v59, v59
	v_sub_f32_e32 v61, v170, v63
	v_exp_f32_e32 v61, v61
	v_sub_f32_e32 v62, v169, v63
	v_sub_f32_e32 v58, v163, v63
	v_exp_f32_e32 v64, v62
	v_sub_f32_e32 v62, v168, v63
	v_exp_f32_e32 v65, v62
	v_exp_f32_e32 v62, v58
	v_add_f32_e32 v60, 0, v59
	v_add_f32_e32 v60, v61, v60
	v_add_f32_e32 v60, v64, v60
	v_add_f32_e32 v163, v65, v60
	v_sub_f32_e32 v60, v166, v63
	v_cmp_neq_f32_e32 vcc, 1.0, v62
	v_exp_f32_e32 v168, v60
	v_sub_f32_e32 v60, v167, v63
	s_cmp_eq_u64 vcc, 0
	v_exp_f32_e32 v169, v60
	v_sub_f32_e32 v60, v164, v63
	s_cselect_b64 vcc, -1, 0
	v_cvt_pk_bf16_f32 v58, v59, v61
	v_cvt_pk_bf16_f32 v59, v64, v65
	v_pk_mul_f32 v[64:65], v[46:47], v[62:63] op_sel_hi:[1,0]
	v_exp_f32_e32 v170, v60
	v_sub_f32_e32 v60, v165, v63
	v_pk_mul_f32 v[164:165], v[48:49], v[62:63] op_sel_hi:[1,0]
	v_cndmask_b32_e32 v46, v64, v46, vcc
	v_exp_f32_e32 v171, v60
	v_cvt_pk_bf16_f32 v60, v168, v169
	v_cvt_pk_bf16_f32 v61, v170, v171
	v_cndmask_b32_e32 v49, v165, v49, vcc
	v_cndmask_b32_e32 v48, v164, v48, vcc
	v_cndmask_b32_e32 v47, v65, v47, vcc
	v_pk_mul_f32 v[64:65], v[62:63], v[52:53] op_sel_hi:[0,1]
	v_cndmask_b32_e32 v52, v64, v52, vcc
	s_waitcnt lgkmcnt(0)
	v_mfma_f32_16x16x32_bf16 v[46:49], v[206:209], v[58:61], v[46:49]
	v_mul_f32_e64 v164, v62, v50
	v_mul_f32_e64 v165, v62, v51
	v_cndmask_b32_e32 v51, v165, v51, vcc
	v_cndmask_b32_e32 v50, v164, v50, vcc
	v_cndmask_b32_e32 v53, v65, v53, vcc
	v_pk_mul_f32 v[64:65], v[62:63], v[44:45] op_sel_hi:[0,1]
	v_cndmask_b32_e32 v44, v64, v44, vcc
	s_nop 0
	v_mfma_f32_16x16x32_bf16 v[50:53], v[210:213], v[58:61], v[50:53]
	v_mul_f32_e64 v164, v62, v42
	v_mul_f32_e64 v165, v62, v43
	v_cndmask_b32_e32 v43, v165, v43, vcc
	v_cndmask_b32_e32 v42, v164, v42, vcc
	v_cndmask_b32_e32 v45, v65, v45, vcc
	v_pk_mul_f32 v[64:65], v[62:63], v[56:57] op_sel_hi:[0,1]
	v_cndmask_b32_e32 v56, v64, v56, vcc
	s_nop 0
	v_mfma_f32_16x16x32_bf16 v[42:45], v[214:217], v[58:61], v[42:45]
	v_mul_f32_e64 v164, v62, v54
	v_mul_f32_e64 v165, v62, v55
	v_cndmask_b32_e32 v55, v165, v55, vcc
	v_cndmask_b32_e32 v54, v164, v54, vcc
	v_cndmask_b32_e32 v57, v65, v57, vcc
	s_add_i32 s42, s42, 32
	s_cmpk_eq_i32 s42, 0xe0
	s_nop 0
	v_mfma_f32_16x16x32_bf16 v[54:57], v[218:221], v[58:61], v[54:57]
	v_add_f32_e32 v58, v168, v163
	v_add_f32_e32 v58, v169, v58
	v_add_f32_e32 v58, v170, v58
	v_add_f32_e32 v58, v171, v58
	v_fmac_f32_e32 v58, v162, v62
	s_cbranch_scc1 .LBB0_837
	v_mov_b32_e32 v163, v63
	v_mov_b32_e32 v162, v58
	s_branch .LBB0_847
